# phase_prep weight transposes: next tile's 8 row loads and 8 gain loads issued back to back with a single wait (the compiler waited vmcnt(0) after every row)
# speedup vs baseline: 1.0088x; 1.0088x over previous
.LBB0_66:
	s_lshr_b32 s2, s39, 7
	v_cvt_f32_ubyte0_e32 v2, s2
	v_rcp_iflag_f32_e32 v2, v2
	s_sub_i32 s26, 0, s2
	s_abs_i32 s25, s38
	s_ashr_i32 s24, s38, 31
	v_mul_f32_e32 v2, 0x4f7ffffe, v2
	v_cvt_u32_f32_e32 v2, v2
	v_mov_b32_e32 v6, 0
	v_mov_b32_e32 v7, 0
	v_mov_b32_e32 v8, 0
	v_readfirstlane_b32 s27, v2
	s_mul_i32 s26, s26, s27
	s_mul_hi_u32 s26, s27, s26
	s_add_i32 s27, s27, s26
	s_mul_hi_u32 s26, s25, s27
	s_mul_i32 s27, s26, s2
	s_sub_i32 s25, s25, s27
	s_add_i32 s42, s26, 1
	s_sub_i32 s27, s25, s2
	s_cmp_ge_u32 s25, s2
	s_cselect_b32 s26, s42, s26
	s_cselect_b32 s25, s27, s25
	s_add_i32 s27, s26, 1
	s_cmp_ge_u32 s25, s2
	s_cselect_b32 s25, s27, s26
	s_xor_b32 s25, s25, s24
	s_sub_i32 s24, s25, s24
	s_mul_i32 s2, s24, s2
	s_sub_i32 s2, s38, s2
	v_lshl_add_u32 v38, s24, 7, v42
	s_lshl_b32 s24, s2, 7
	v_or_b32_e32 v2, s24, v41
	s_ashr_i32 s25, s24, 31
	v_cmp_gt_i32_e32 vcc, s41, v2
	v_mov_b32_e32 v2, 0
	v_mov_b32_e32 v3, 0
	v_mov_b32_e32 v4, 0
	v_mov_b32_e32 v5, 0
	v_mov_b32_e32 v6, 0
	v_mov_b32_e32 v7, 0
	v_mov_b32_e32 v8, 0
	v_mov_b32_e32 v9, 0
	v_mov_b32_e32 v10, 0
	v_mov_b32_e32 v11, 0
	v_mov_b32_e32 v12, 0
	v_mov_b32_e32 v13, 0
	v_mov_b32_e32 v14, 0
	v_mov_b32_e32 v15, 0
	v_mov_b32_e32 v16, 0
	v_mov_b32_e32 v17, 0
	v_mov_b32_e32 v18, 0
	v_mov_b32_e32 v19, 0
	v_mov_b32_e32 v20, 0
	v_mov_b32_e32 v21, 0
	v_mov_b32_e32 v22, 0
	v_mov_b32_e32 v23, 0
	v_mov_b32_e32 v24, 0
	v_mov_b32_e32 v25, 0
	v_mov_b32_e32 v26, 0
	v_mov_b32_e32 v27, 0
	v_mov_b32_e32 v28, 0
	v_mov_b32_e32 v29, 0
	v_mov_b32_e32 v30, 0
	v_mov_b32_e32 v31, 0
	v_mov_b32_e32 v32, 0
	v_mov_b32_e32 v33, 0
	s_and_saveexec_b64 s[26:27], vcc
	s_cbranch_execz .LBB0_48
	v_mad_i64_i32 v[202:203], s[42:43], v38, s41, 0
	v_lshl_add_u64 v[202:203], v[202:203], 2, s[20:21]
	v_lshl_add_u64 v[202:203], s[24:25], 2, v[202:203]
	v_lshl_add_u64 v[202:203], v[202:203], 0, v[34:35]
	global_load_dwordx4 v[6:9], v[202:203], off
	v_add_u32_e32 v200, 16, v38
	v_mad_i64_i32 v[202:203], s[42:43], v200, s41, 0
	v_lshl_add_u64 v[202:203], v[202:203], 2, s[20:21]
	v_lshl_add_u64 v[202:203], s[24:25], 2, v[202:203]
	v_lshl_add_u64 v[202:203], v[202:203], 0, v[34:35]
	global_load_dwordx4 v[2:5], v[202:203], off
	v_add_u32_e32 v200, 32, v38
	v_mad_i64_i32 v[202:203], s[42:43], v200, s41, 0
	v_lshl_add_u64 v[202:203], v[202:203], 2, s[20:21]
	v_lshl_add_u64 v[202:203], s[24:25], 2, v[202:203]
	v_lshl_add_u64 v[202:203], v[202:203], 0, v[34:35]
	global_load_dwordx4 v[14:17], v[202:203], off
	v_add_u32_e32 v200, 48, v38
	v_mad_i64_i32 v[202:203], s[42:43], v200, s41, 0
	v_lshl_add_u64 v[202:203], v[202:203], 2, s[20:21]
	v_lshl_add_u64 v[202:203], s[24:25], 2, v[202:203]
	v_lshl_add_u64 v[202:203], v[202:203], 0, v[34:35]
	global_load_dwordx4 v[10:13], v[202:203], off
	v_add_u32_e32 v200, 64, v38
	v_mad_i64_i32 v[202:203], s[42:43], v200, s41, 0
	v_lshl_add_u64 v[202:203], v[202:203], 2, s[20:21]
	v_lshl_add_u64 v[202:203], s[24:25], 2, v[202:203]
	v_lshl_add_u64 v[202:203], v[202:203], 0, v[34:35]
	global_load_dwordx4 v[22:25], v[202:203], off
	v_add_u32_e32 v200, 80, v38
	v_mad_i64_i32 v[202:203], s[42:43], v200, s41, 0
	v_lshl_add_u64 v[202:203], v[202:203], 2, s[20:21]
	v_lshl_add_u64 v[202:203], s[24:25], 2, v[202:203]
	v_lshl_add_u64 v[202:203], v[202:203], 0, v[34:35]
	global_load_dwordx4 v[18:21], v[202:203], off
	v_add_u32_e32 v200, 96, v38
	v_mad_i64_i32 v[202:203], s[42:43], v200, s41, 0
	v_lshl_add_u64 v[202:203], v[202:203], 2, s[20:21]
	v_lshl_add_u64 v[202:203], s[24:25], 2, v[202:203]
	v_lshl_add_u64 v[202:203], v[202:203], 0, v[34:35]
	global_load_dwordx4 v[30:33], v[202:203], off
	v_add_u32_e32 v200, 112, v38
	v_mad_i64_i32 v[202:203], s[42:43], v200, s41, 0
	v_lshl_add_u64 v[202:203], v[202:203], 2, s[20:21]
	v_lshl_add_u64 v[202:203], s[24:25], 2, v[202:203]
	v_lshl_add_u64 v[202:203], v[202:203], 0, v[34:35]
	global_load_dwordx4 v[26:29], v[202:203], off
	s_cmp_eq_u64 s[22:23], 0
	s_cbranch_scc1 .LBB0_48
	v_ashrrev_i32_e32 v39, 31, v38
	v_lshl_add_u64 v[202:203], v[38:39], 2, s[22:23]
	global_load_dword v210, v[202:203], off
	global_load_dword v211, v[202:203], off offset:64
	global_load_dword v212, v[202:203], off offset:128
	global_load_dword v213, v[202:203], off offset:192
	global_load_dword v214, v[202:203], off offset:256
	global_load_dword v215, v[202:203], off offset:320
	global_load_dword v216, v[202:203], off offset:384
	global_load_dword v217, v[202:203], off offset:448
	s_waitcnt vmcnt(0)
	v_mul_f32_e32 v6, v6, v210
	v_mul_f32_e32 v7, v7, v210
	v_mul_f32_e32 v8, v8, v210
	v_mul_f32_e32 v9, v9, v210
	v_mul_f32_e32 v2, v2, v211
	v_mul_f32_e32 v3, v3, v211
	v_mul_f32_e32 v4, v4, v211
	v_mul_f32_e32 v5, v5, v211
	v_mul_f32_e32 v14, v14, v212
	v_mul_f32_e32 v15, v15, v212
	v_mul_f32_e32 v16, v16, v212
	v_mul_f32_e32 v17, v17, v212
	v_mul_f32_e32 v10, v10, v213
	v_mul_f32_e32 v11, v11, v213
	v_mul_f32_e32 v12, v12, v213
	v_mul_f32_e32 v13, v13, v213
	v_mul_f32_e32 v22, v22, v214
	v_mul_f32_e32 v23, v23, v214
	v_mul_f32_e32 v24, v24, v214
	v_mul_f32_e32 v25, v25, v214
	v_mul_f32_e32 v18, v18, v215
	v_mul_f32_e32 v19, v19, v215
	v_mul_f32_e32 v20, v20, v215
	v_mul_f32_e32 v21, v21, v215
	v_mul_f32_e32 v30, v30, v216
	v_mul_f32_e32 v31, v31, v216
	v_mul_f32_e32 v32, v32, v216
	v_mul_f32_e32 v33, v33, v216
	v_mul_f32_e32 v26, v26, v217
	v_mul_f32_e32 v27, v27, v217
	v_mul_f32_e32 v28, v28, v217
	v_mul_f32_e32 v29, v29, v217
	s_branch .LBB0_48
